# sp3 item prologue: K-rotation load groups prefetched into free R-state registers, first V-tile load no longer serialized ahead of the other seven
# speedup vs baseline: 1.0072x; 1.0072x over previous
; #define LAS __attribute__((address_space(3)))
; __device__ __forceinline__ unsigned pk2(float lo, float hi) { unsigned r; asm("v_cvt_pk_bf16_f32 %0, %1, %2" : "=v"(r) : "v"(lo), "v"(hi)); return r; }
; __device__ __forceinline__ float bflo(unsigned u) { return __uint_as_float(u << 16); }
; __device__ __forceinline__ float bfhi(unsigned u) { return __uint_as_float(u & 0xffff0000u); }
; __device__ __forceinline__ float log2_gamma(int h) { return log2f(1.0f - exp2f(-5.0f - (float)h)); }
; template <bool SCALE>
; __device__ __forceinline__ void load_tile_T(const bf16_t* src, LAS bf16_t* T, int lane, float sc0, float scmul) {
;     const int cr = lane >> 3, dc = lane & 7;
;     u32x4 v[8];
; #pragma unroll
;     for (int i = 0; i < 8; ++i) v[i] = *(const u32x4*)(src + (size_t)(cr + 8 * i) * INWP + 8 * dc);
; #pragma unroll
;     for (int i = 0; i < 8; ++i) { const int row = cr + 8 * i; u32x4 w = v[i];
;         if (SCALE) { const float s = sc0 * __builtin_amdgcn_exp2f(scmul * (float)row);
;             w.x = pk2(bflo(w.x) * s, bfhi(w.x) * s); w.y = pk2(bflo(w.y) * s, bfhi(w.y) * s); w.z = pk2(bflo(w.z) * s, bfhi(w.z) * s); w.w = pk2(bflo(w.w) * s, bfhi(w.w) * s); }
;         LAS bf16_t* t = T + (8 * dc) * TLD + row;
;         t[0 * TLD] = (bf16_t)(w.x & 0xffff); t[1 * TLD] = (bf16_t)(w.x >> 16); t[2 * TLD] = (bf16_t)(w.y & 0xffff); t[3 * TLD] = (bf16_t)(w.y >> 16);
;         t[4 * TLD] = (bf16_t)(w.z & 0xffff); t[5 * TLD] = (bf16_t)(w.z >> 16); t[6 * TLD] = (bf16_t)(w.w & 0xffff); t[7 * TLD] = (bf16_t)(w.w >> 16); }
; __device__ __forceinline__ void retout_item(const bf16_t* hbuf, const float* rot, const float* kvbuf, const float* normg, bf16_t* mixed, LAS bf16_t* vT, int item, int lane) {
;     const int bh = item / NCHUNK, n = item % NCHUNK, b = bh / 6, h = bh % 6; const size_t t0 = (size_t)b * SEQ + (size_t)n * 64;
;     const int r = lane & 15, q = lane >> 4; const float l2g = log2_gamma(h);
;     load_tile_T<false>(hbuf + t0 * INWP + C_RV + h * 64, vT, lane, 0.f, 0.f);
.LBB0_175:
	s_ashr_i32 s1, s0, 31
	s_lshr_b32 s12, s1, 24
	s_add_i32 s12, s0, s12
	s_ashr_i32 s17, s12, 8
	s_and_b32 s12, s12, 0xffffff00
	s_sub_i32 s20, s0, s12
	s_mul_hi_i32 s12, s0, 0x2aaaaaab
	s_lshr_b32 s15, s12, 31
	s_ashr_i32 s12, s12, 8
	s_add_i32 s22, s12, s15
	s_mul_hi_i32 s12, s17, 0x2aaaaaab
	s_lshr_b32 s15, s12, 31
	s_add_i32 s12, s12, s15
	s_mul_i32 s12, s12, 6
	s_sub_i32 s15, s17, s12
	v_cvt_f32_i32_e32 v0, s15
	s_mov_b32 s12, 0xc2fc0000
	s_ashr_i32 s23, s22, 31
	s_ashr_i32 s21, s20, 31
	v_sub_f32_e32 v0, 0xc0a00000, v0
	v_cmp_gt_f32_e32 vcc, s12, v0
	s_lshl_b64 s[22:23], s[22:23], 14
	s_lshl_b64 s[26:27], s[20:21], 6
	v_cndmask_b32_e32 v1, 0, v229, vcc
	v_add_f32_e32 v0, v0, v1
	s_add_u32 s22, s22, s26
	v_exp_f32_e32 v0, v0
	s_addc_u32 s21, s23, s27
	s_and_b64 s[26:27], vcc, exec
	s_cselect_b32 s23, 0xffffffc0, 0
	v_ldexp_f32 v0, v0, s23
	s_mul_i32 s23, s21, 0x1800
	s_mul_hi_u32 s26, s22, 0x1800
	s_add_i32 s26, s26, s23
	s_mul_i32 s23, s22, 0x1800
	s_add_u32 s23, s42, s23
	s_addc_u32 s27, s43, s26
	s_lshl_b32 s38, s15, 6
	s_ashr_i32 s39, s38, 31
	s_lshl_b64 s[36:37], s[38:39], 1
	s_add_u32 s26, s23, s36
	s_addc_u32 s27, s27, s37
	v_sub_f32_e32 v53, 1.0, v0
	v_lshl_add_u64 v[0:1], s[26:27], 0, v[32:33]
	v_mov_b32_e32 v85, v33
	v_lshl_add_u64 v[24:25], v[0:1], 0, v[84:85]
	s_movk_i32 s15, 0x1000
	v_add_co_u32_e32 v0, vcc, s15, v24
	s_mov_b32 s15, 0xd000
	s_nop 0
	v_addc_co_u32_e32 v1, vcc, 0, v25, vcc
	global_load_dwordx4 v[232:235], v[0:1], off offset:256
	v_or_b32_e32 v52, s22, v60
	v_mov_b64_e32 v[44:45], s[42:43]
	v_mov_b32_e32 v87, v33
	v_mov_b32_e32 v89, v33
	v_mov_b32_e32 v91, v33
	v_mov_b32_e32 v93, v33
	v_mov_b32_e32 v95, v33
	s_mov_b32 s12, 0
	v_lshl_add_u64 v[96:97], s[38:39], 2, v[76:77]
	v_add_co_u32_e32 v0, vcc, s15, v24
	s_mov_b32 s15, 0x19000
	s_nop 0
	v_addc_co_u32_e32 v1, vcc, 0, v25, vcc
	global_load_dwordx4 v[0:3], v[0:1], off offset:256
	v_add_co_u32_e32 v4, vcc, s15, v24
	s_mov_b32 s15, 0x25000
	s_nop 0
	v_addc_co_u32_e32 v5, vcc, 0, v25, vcc
	global_load_dwordx4 v[4:7], v[4:5], off offset:256
	v_add_co_u32_e32 v8, vcc, s15, v24
	s_mov_b32 s15, 0x31000
	s_nop 0
	v_addc_co_u32_e32 v9, vcc, 0, v25, vcc
	global_load_dwordx4 v[8:11], v[8:9], off offset:256
	v_add_co_u32_e32 v12, vcc, s15, v24
	s_mov_b32 s15, 0x3d000
	s_nop 0
	v_addc_co_u32_e32 v13, vcc, 0, v25, vcc
	global_load_dwordx4 v[12:15], v[12:13], off offset:256
	v_add_co_u32_e32 v16, vcc, s15, v24
	s_mov_b32 s15, 0x49000
	s_nop 0
	v_addc_co_u32_e32 v17, vcc, 0, v25, vcc
	global_load_dwordx4 v[16:19], v[16:17], off offset:256
	v_add_co_u32_e32 v20, vcc, s15, v24
	s_mov_b32 s15, 0x55000
	s_nop 0
	v_addc_co_u32_e32 v21, vcc, 0, v25, vcc
	global_load_dwordx4 v[20:23], v[20:21], off offset:256
	v_add_co_u32_e32 v24, vcc, s15, v24
	s_lshl_b32 s15, s20, 6
	s_nop 0
	v_addc_co_u32_e32 v25, vcc, 0, v25, vcc
	global_load_dwordx4 v[24:27], v[24:25], off offset:256
	s_waitcnt vmcnt(7)
	ds_write_b16 v39, v232
	ds_write_b16_d16_hi v39, v232 offset:144
	ds_write_b16 v39, v233 offset:288
	ds_write_b16_d16_hi v39, v233 offset:432
	ds_write_b16 v39, v234 offset:576
	ds_write_b16_d16_hi v39, v234 offset:720
	ds_write_b16 v39, v235 offset:864
	ds_write_b16_d16_hi v39, v235 offset:1008
	v_cmp_gt_f32_e32 vcc, s33, v53
	s_waitcnt vmcnt(6)
	ds_write_b16 v39, v0 offset:16
	ds_write_b16_d16_hi v39, v0 offset:160
	ds_write_b16 v39, v1 offset:304
	ds_write_b16_d16_hi v39, v1 offset:448
	ds_write_b16 v39, v2 offset:592
	ds_write_b16_d16_hi v39, v2 offset:736
	ds_write_b16 v39, v3 offset:880
	ds_write_b16_d16_hi v39, v3 offset:1024
	s_waitcnt vmcnt(5)
	ds_write_b16 v39, v4 offset:32
	ds_write_b16_d16_hi v39, v4 offset:176
	ds_write_b16 v39, v5 offset:320
	ds_write_b16_d16_hi v39, v5 offset:464
	ds_write_b16 v39, v6 offset:608
	ds_write_b16_d16_hi v39, v6 offset:752
	ds_write_b16 v39, v7 offset:896
	ds_write_b16_d16_hi v39, v7 offset:1040
	s_waitcnt vmcnt(4)
	ds_write_b16 v39, v8 offset:48
	ds_write_b16_d16_hi v39, v8 offset:192
	ds_write_b16 v39, v9 offset:336
	ds_write_b16_d16_hi v39, v9 offset:480
	ds_write_b16 v39, v10 offset:624
	ds_write_b16_d16_hi v39, v10 offset:768
	ds_write_b16 v39, v11 offset:912
	ds_write_b16_d16_hi v39, v11 offset:1056
	s_waitcnt vmcnt(3)
	ds_write_b16 v39, v12 offset:64
	ds_write_b16_d16_hi v39, v12 offset:208
	ds_write_b16 v39, v13 offset:352
	ds_write_b16_d16_hi v39, v13 offset:496
	ds_write_b16 v39, v14 offset:640
	ds_write_b16_d16_hi v39, v14 offset:784
	ds_write_b16 v39, v15 offset:928
	ds_write_b16_d16_hi v39, v15 offset:1072
	s_waitcnt vmcnt(2)
	ds_write_b16 v39, v16 offset:80
	ds_write_b16_d16_hi v39, v16 offset:224
	ds_write_b16 v39, v17 offset:368
	ds_write_b16_d16_hi v39, v17 offset:512
	ds_write_b16 v39, v18 offset:656
	ds_write_b16_d16_hi v39, v18 offset:800
	ds_write_b16 v39, v19 offset:944
	ds_write_b16_d16_hi v39, v19 offset:1088
	s_waitcnt vmcnt(1)
	ds_write_b16 v39, v20 offset:96
	ds_write_b16_d16_hi v39, v20 offset:240
	ds_write_b16 v39, v21 offset:384
	ds_write_b16_d16_hi v39, v21 offset:528
	ds_write_b16 v39, v22 offset:672
	ds_write_b16_d16_hi v39, v22 offset:816
	ds_write_b16 v39, v23 offset:960
	ds_write_b16_d16_hi v39, v23 offset:1104
	s_waitcnt vmcnt(0)
; #define LAS __attribute__((address_space(3)))
; __device__ __forceinline__ unsigned pk2(float lo, float hi) { unsigned r; asm("v_cvt_pk_bf16_f32 %0, %1, %2" : "=v"(r) : "v"(lo), "v"(hi)); return r; }
; __device__ __forceinline__ float bflo(unsigned u) { return __uint_as_float(u << 16); }
; __device__ __forceinline__ float bfhi(unsigned u) { return __uint_as_float(u & 0xffff0000u); }
; __device__ __forceinline__ void rot8(u32x4 x1, u32x4 x2, const float* cs, const float* sn, float sc, u32x4& o1, u32x4& o2) {
;     const f32x4 c0 = *(const f32x4*)cs, c1 = *(const f32x4*)(cs + 4), s0 = *(const f32x4*)sn, s1 = *(const f32x4*)(sn + 4);
;     float a[8], b[8], c[8], s[8];
;     a[0] = bflo(x1.x); a[1] = bfhi(x1.x); a[2] = bflo(x1.y); a[3] = bfhi(x1.y); a[4] = bflo(x1.z); a[5] = bfhi(x1.z); a[6] = bflo(x1.w); a[7] = bfhi(x1.w);
;     b[0] = bflo(x2.x); b[1] = bfhi(x2.x); b[2] = bflo(x2.y); b[3] = bfhi(x2.y); b[4] = bflo(x2.z); b[5] = bfhi(x2.z); b[6] = bflo(x2.w); b[7] = bfhi(x2.w);
; #pragma unroll
;     for (int i = 0; i < 4; ++i) { c[i] = c0[i]; c[4 + i] = c1[i]; s[i] = s0[i]; s[4 + i] = s1[i]; }
;     float p[8], q[8];
; #pragma unroll
;     for (int i = 0; i < 8; ++i) { p[i] = (a[i] * c[i] - b[i] * s[i]) * sc; q[i] = (a[i] * s[i] + b[i] * c[i]) * sc; }
;     o1.x = pk2(p[0], p[1]); o1.y = pk2(p[2], p[3]); o1.z = pk2(p[4], p[5]); o1.w = pk2(p[6], p[7]);
;     o2.x = pk2(q[0], q[1]); o2.y = pk2(q[2], q[3]); o2.z = pk2(q[4], q[5]); o2.w = pk2(q[6], q[7]);
; }
; __device__ __forceinline__ void retout_item(const bf16_t* hbuf, const float* rot, const float* kvbuf, const float* normg, bf16_t* mixed, LAS bf16_t* vT, int item, int lane) {
;     ...
;     bf16x8 kf[4][2]; LAS bf16_t* RT = vT + 64 * TLD;
; #pragma unroll
;     for (int mt = 0; mt < 4; ++mt) { const int row = 16 * mt + r; const bf16_t* kp = hbuf + (t0 + row) * INWP + C_RK + h * 64 + 8 * q; const int pos = n * 64 + row; u32x4 o1, o2;
;         rot8(*(const u32x4*)kp, *(const u32x4*)(kp + 32), cs + (size_t)pos * 32 + 8 * q, sn + (size_t)pos * 32 + 8 * q, 0.125f, o1, o2); kf[mt][0] = as_bf16x8(o1); kf[mt][1] = as_bf16x8(o2); }
	ds_write_b16 v39, v24 offset:112
	ds_write_b16_d16_hi v39, v24 offset:256
	ds_write_b16 v39, v25 offset:400
	ds_write_b16_d16_hi v39, v25 offset:544
	ds_write_b16 v39, v26 offset:688
	ds_write_b16_d16_hi v39, v26 offset:832
	ds_write_b16 v39, v27 offset:976
	ds_write_b16_d16_hi v39, v27 offset:1120
	v_mad_u64_u32 v[0:1], s[26:27], v52, s5, v[44:45]
	v_or_b32_e32 v8, s15, v60
	v_mad_i32_i24 v1, s21, v207, v1
	v_ashrrev_i32_e32 v9, 31, v8
	v_lshl_add_u64 v[0:1], v[0:1], 0, s[36:37]
	v_lshlrev_b64 v[8:9], 7, v[8:9]
	v_lshl_add_u64 v[4:5], v[0:1], 0, v[86:87]
	v_lshl_add_u64 v[12:13], v[64:65], 0, v[8:9]
	v_lshl_add_u64 v[20:21], v[66:67], 0, v[8:9]
	v_mov_b64_e32 v[152:153], v[4:5]
	global_load_dwordx4 v[0:3], v[4:5], off offset:3584
	s_nop 0
	global_load_dwordx4 v[4:7], v[4:5], off offset:3648
	s_nop 0
	v_mov_b64_e32 v[154:155], v[12:13]
	global_load_dwordx4 v[8:11], v[12:13], off offset:16
	global_load_dwordx4 v[16:19], v[12:13], off
	s_nop 0
	v_mov_b64_e32 v[156:157], v[20:21]
	global_load_dwordx4 v[12:15], v[20:21], off offset:16
	s_nop 0
	global_load_dwordx4 v[20:23], v[20:21], off
	s_mov_b32 s98, 0x18000
	s_mov_b32 s99, 0
	v_lshl_add_u64 v[158:159], s[98:99], 0, v[152:153]
	global_load_dwordx4 v[172:175], v[158:159], off offset:3584
	global_load_dwordx4 v[176:179], v[158:159], off offset:3648
	global_load_dwordx4 v[180:183], v[154:155], off offset:2064
	global_load_dwordx4 v[184:187], v[154:155], off offset:2048
	global_load_dwordx4 v[188:191], v[156:157], off offset:2064
	global_load_dwordx4 v[192:195], v[156:157], off offset:2048
	s_mov_b32 s98, 0x30000
	s_mov_b32 s99, 0
	v_lshl_add_u64 v[158:159], s[98:99], 0, v[152:153]
	global_load_dwordx4 v[196:199], v[158:159], off offset:3584
	global_load_dwordx4 v[200:203], v[158:159], off offset:3648
	s_mov_b32 s98, 0x1000
	v_lshl_add_u64 v[158:159], s[98:99], 0, v[154:155]
	global_load_dwordx4 v[212:215], v[158:159], off offset:16
	global_load_dwordx4 v[216:219], v[158:159], off
	v_lshl_add_u64 v[158:159], s[98:99], 0, v[156:157]
	global_load_dwordx4 v[220:223], v[158:159], off offset:16
	global_load_dwordx4 v[224:227], v[158:159], off
	s_waitcnt vmcnt(14)
	v_mov_b32_e32 v27, v16
	v_lshlrev_b32_e32 v25, 16, v0
	v_lshlrev_b32_e32 v24, 16, v4
	s_waitcnt vmcnt(12)
	v_mov_b32_e32 v26, v20
	v_pk_mul_f32 v[26:27], v[26:27], v[24:25]
	s_nop 0
	v_sub_f32_e32 v26, v27, v26
	v_mul_f32_e32 v28, 0x3e000000, v26
	v_mov_b32_e32 v26, v16
	v_mov_b32_e32 v27, v20
	v_pk_mul_f32 v[24:25], v[26:27], v[24:25]
	v_mov_b32_e32 v20, v17
	v_add_f32_e32 v16, v24, v25
	v_mul_f32_e32 v29, 0x3e000000, v16
	v_and_b32_e32 v25, 0xffff0000, v0
	v_and_b32_e32 v24, 0xffff0000, v4
	v_mov_b32_e32 v16, v21
	v_pk_mul_f32 v[26:27], v[16:17], v[24:25]
	v_pk_mul_f32 v[16:17], v[20:21], v[24:25]
	v_sub_f32_e32 v0, v27, v26
	v_mul_f32_e32 v26, 0x3e000000, v0
	v_add_f32_e32 v0, v16, v17
	v_lshlrev_b32_e32 v17, 16, v1
	v_lshlrev_b32_e32 v16, 16, v5
	v_mov_b32_e32 v20, v22
	v_mov_b32_e32 v21, v18
	v_pk_mul_f32 v[20:21], v[20:21], v[16:17]
	v_mul_f32_e32 v24, 0x3e000000, v0
	v_sub_f32_e32 v0, v21, v20
	v_mov_b32_e32 v20, v18
	v_mov_b32_e32 v21, v22
	v_pk_mul_f32 v[16:17], v[20:21], v[16:17]
	v_mul_f32_e32 v25, 0x3e000000, v0
	v_add_f32_e32 v0, v16, v17
	v_mul_f32_e32 v16, 0x3e000000, v0
	v_and_b32_e32 v1, 0xffff0000, v1
	v_and_b32_e32 v0, 0xffff0000, v5
	v_mov_b32_e32 v18, v23
	v_mov_b32_e32 v22, v19
	v_pk_mul_f32 v[4:5], v[18:19], v[0:1]
	v_pk_mul_f32 v[0:1], v[22:23], v[0:1]
	v_sub_f32_e32 v4, v5, v4
	v_add_f32_e32 v0, v0, v1
	v_mul_f32_e32 v17, 0x3e000000, v4
	v_mul_f32_e32 v18, 0x3e000000, v0
	v_lshlrev_b32_e32 v1, 16, v2
	v_lshlrev_b32_e32 v0, 16, v6
	v_mov_b32_e32 v4, v12
	v_mov_b32_e32 v5, v8
	v_pk_mul_f32 v[4:5], v[4:5], v[0:1]
	s_nop 0
	v_sub_f32_e32 v4, v5, v4
	v_mul_f32_e32 v19, 0x3e000000, v4
	v_mov_b32_e32 v4, v8
	v_mov_b32_e32 v5, v12
	v_pk_mul_f32 v[0:1], v[4:5], v[0:1]
	v_mov_b32_e32 v8, v13
	v_add_f32_e32 v0, v0, v1
	v_mul_f32_e32 v20, 0x3e000000, v0
	v_and_b32_e32 v1, 0xffff0000, v2
	v_and_b32_e32 v0, 0xffff0000, v6
	v_mov_b32_e32 v12, v9
	v_pk_mul_f32 v[4:5], v[8:9], v[0:1]
	v_pk_mul_f32 v[0:1], v[12:13], v[0:1]
	v_sub_f32_e32 v2, v5, v4
	v_add_f32_e32 v0, v0, v1
	v_mul_f32_e32 v8, 0x3e000000, v0
	v_lshlrev_b32_e32 v1, 16, v3
	v_lshlrev_b32_e32 v0, 16, v7
	v_mov_b32_e32 v4, v14
	v_mov_b32_e32 v5, v10
	v_pk_mul_f32 v[4:5], v[4:5], v[0:1]
	v_mul_f32_e32 v6, 0x3e000000, v2
	v_sub_f32_e32 v2, v5, v4
	v_mov_b32_e32 v4, v10
	v_mov_b32_e32 v5, v14
	v_pk_mul_f32 v[0:1], v[4:5], v[0:1]
	v_mov_b32_e32 v10, v15
	v_add_f32_e32 v0, v0, v1
	v_mul_f32_e32 v12, 0x3e000000, v0
	v_and_b32_e32 v1, 0xffff0000, v3
	v_and_b32_e32 v0, 0xffff0000, v7
	v_mul_f32_e32 v9, 0x3e000000, v2
	v_pk_mul_f32 v[2:3], v[10:11], v[0:1]
	v_mov_b32_e32 v14, v11
	v_sub_f32_e32 v2, v3, v2
	v_mul_f32_e32 v3, 0x3e000000, v2
	v_cvt_pk_bf16_f32 v2, v19, v6
	v_cvt_pk_bf16_f32 v6, v20, v8
	v_or_b32_e32 v8, s22, v68
	v_pk_mul_f32 v[0:1], v[14:15], v[0:1]
	v_cvt_pk_bf16_f32 v3, v9, v3
	v_cvt_pk_bf16_f32 v5, v16, v18
	v_mad_u64_u32 v[8:9], s[26:27], v8, s5, v[44:45]
	v_or_b32_e32 v16, s15, v68
	v_add_f32_e32 v0, v0, v1
	v_cvt_pk_bf16_f32 v1, v25, v17
	v_mad_i32_i24 v9, s21, v207, v9
	v_ashrrev_i32_e32 v17, 31, v16
	v_mul_f32_e32 v7, 0x3e000000, v0
	v_lshl_add_u64 v[8:9], v[8:9], 0, s[36:37]
	v_lshlrev_b64 v[16:17], 7, v[16:17]
	v_cvt_pk_bf16_f32 v0, v28, v26
	v_cvt_pk_bf16_f32 v4, v29, v24
	v_cvt_pk_bf16_f32 v7, v12, v7
	v_lshl_add_u64 v[12:13], v[8:9], 0, v[86:87]
	v_lshl_add_u64 v[20:21], v[64:65], 0, v[16:17]
	v_lshl_add_u64 v[28:29], v[66:67], 0, v[16:17]
	s_waitcnt vmcnt(6)
; __device__ __forceinline__ unsigned pk2(float lo, float hi) { unsigned r; asm("v_cvt_pk_bf16_f32 %0, %1, %2" : "=v"(r) : "v"(lo), "v"(hi)); return r; }
; __device__ __forceinline__ float bflo(unsigned u) { return __uint_as_float(u << 16); }
; __device__ __forceinline__ float bfhi(unsigned u) { return __uint_as_float(u & 0xffff0000u); }
; __device__ __forceinline__ void rot8(u32x4 x1, u32x4 x2, const float* cs, const float* sn, float sc, u32x4& o1, u32x4& o2) {
;     const f32x4 c0 = *(const f32x4*)cs, c1 = *(const f32x4*)(cs + 4), s0 = *(const f32x4*)sn, s1 = *(const f32x4*)(sn + 4);
;     float a[8], b[8], c[8], s[8];
;     a[0] = bflo(x1.x); a[1] = bfhi(x1.x); a[2] = bflo(x1.y); a[3] = bfhi(x1.y); a[4] = bflo(x1.z); a[5] = bfhi(x1.z); a[6] = bflo(x1.w); a[7] = bfhi(x1.w);
;     b[0] = bflo(x2.x); b[1] = bfhi(x2.x); b[2] = bflo(x2.y); b[3] = bfhi(x2.y); b[4] = bflo(x2.z); b[5] = bfhi(x2.z); b[6] = bflo(x2.w); b[7] = bfhi(x2.w);
; #pragma unroll
;     for (int i = 0; i < 4; ++i) { c[i] = c0[i]; c[4 + i] = c1[i]; s[i] = s0[i]; s[4 + i] = s1[i]; }
;     float p[8], q[8];
; #pragma unroll
;     for (int i = 0; i < 8; ++i) { p[i] = (a[i] * c[i] - b[i] * s[i]) * sc; q[i] = (a[i] * s[i] + b[i] * c[i]) * sc; }
;     o1.x = pk2(p[0], p[1]); o1.y = pk2(p[2], p[3]); o1.z = pk2(p[4], p[5]); o1.w = pk2(p[6], p[7]);
;     o2.x = pk2(q[0], q[1]); o2.y = pk2(q[2], q[3]); o2.z = pk2(q[4], q[5]); o2.w = pk2(q[6], q[7]);
; }
; __device__ __forceinline__ void retout_item(const bf16_t* hbuf, const float* rot, const float* kvbuf, const float* normg, bf16_t* mixed, LAS bf16_t* vT, int item, int lane) {
;     ...
;     for (int mt = 0; mt < 4; ++mt) { const int row = 16 * mt + r; const bf16_t* kp = hbuf + (t0 + row) * INWP + C_RK + h * 64 + 8 * q; const int pos = n * 64 + row; u32x4 o1, o2;
;         rot8(*(const u32x4*)kp, *(const u32x4*)(kp + 32), cs + (size_t)pos * 32 + 8 * q, sn + (size_t)pos * 32 + 8 * q, 0.125f, o1, o2); kf[mt][0] = as_bf16x8(o1); kf[mt][1] = as_bf16x8(o2); }
	v_mov_b64_e32 v[8:9], v[172:173]
	v_mov_b64_e32 v[10:11], v[174:175]
	v_mov_b64_e32 v[12:13], v[176:177]
	v_mov_b64_e32 v[14:15], v[178:179]
	v_mov_b64_e32 v[16:17], v[180:181]
	v_mov_b64_e32 v[18:19], v[182:183]
	v_mov_b64_e32 v[24:25], v[184:185]
	v_mov_b64_e32 v[26:27], v[186:187]
	v_mov_b64_e32 v[20:21], v[188:189]
	v_mov_b64_e32 v[22:23], v[190:191]
	v_mov_b64_e32 v[28:29], v[192:193]
	v_mov_b64_e32 v[30:31], v[194:195]
	s_mov_b32 s98, 0x48000
	s_mov_b32 s99, 0
	v_lshl_add_u64 v[158:159], s[98:99], 0, v[152:153]
	global_load_dwordx4 v[172:175], v[158:159], off offset:3584
	global_load_dwordx4 v[176:179], v[158:159], off offset:3648
	s_mov_b32 s98, 0x1800
	v_lshl_add_u64 v[158:159], s[98:99], 0, v[154:155]
	global_load_dwordx4 v[180:183], v[158:159], off offset:16
	global_load_dwordx4 v[184:187], v[158:159], off
	v_lshl_add_u64 v[158:159], s[98:99], 0, v[156:157]
	global_load_dwordx4 v[188:191], v[158:159], off offset:16
	global_load_dwordx4 v[192:195], v[158:159], off
	v_lshlrev_b32_e32 v35, 16, v8
	v_lshlrev_b32_e32 v34, 16, v12
	v_mov_b32_e32 v36, v28
	v_mov_b32_e32 v37, v24
	v_pk_mul_f32 v[36:37], v[36:37], v[34:35]
	s_nop 0
	v_sub_f32_e32 v36, v37, v36
	v_mul_f32_e32 v40, 0x3e000000, v36
	v_mov_b32_e32 v36, v24
	v_mov_b32_e32 v37, v28
	v_pk_mul_f32 v[34:35], v[36:37], v[34:35]
	v_mov_b32_e32 v28, v25
	v_add_f32_e32 v24, v34, v35
	v_mul_f32_e32 v41, 0x3e000000, v24
	v_and_b32_e32 v35, 0xffff0000, v8
	v_and_b32_e32 v34, 0xffff0000, v12
	v_mov_b32_e32 v24, v29
	v_pk_mul_f32 v[36:37], v[24:25], v[34:35]
	v_pk_mul_f32 v[24:25], v[28:29], v[34:35]
	v_sub_f32_e32 v8, v37, v36
	v_mul_f32_e32 v36, 0x3e000000, v8
	v_add_f32_e32 v8, v24, v25
	v_lshlrev_b32_e32 v25, 16, v9
	v_lshlrev_b32_e32 v24, 16, v13
	v_mov_b32_e32 v28, v30
	v_mov_b32_e32 v29, v26
	v_pk_mul_f32 v[28:29], v[28:29], v[24:25]
	v_mul_f32_e32 v34, 0x3e000000, v8
	v_sub_f32_e32 v8, v29, v28
	v_mov_b32_e32 v28, v26
	v_mov_b32_e32 v29, v30
	v_pk_mul_f32 v[24:25], v[28:29], v[24:25]
	v_mul_f32_e32 v35, 0x3e000000, v8
	v_add_f32_e32 v8, v24, v25
	v_mul_f32_e32 v24, 0x3e000000, v8
	v_and_b32_e32 v9, 0xffff0000, v9
	v_and_b32_e32 v8, 0xffff0000, v13
	v_mov_b32_e32 v26, v31
	v_mov_b32_e32 v30, v27
	v_pk_mul_f32 v[12:13], v[26:27], v[8:9]
	v_pk_mul_f32 v[8:9], v[30:31], v[8:9]
	v_sub_f32_e32 v12, v13, v12
	v_add_f32_e32 v8, v8, v9
	v_mul_f32_e32 v25, 0x3e000000, v12
	v_mul_f32_e32 v26, 0x3e000000, v8
	v_lshlrev_b32_e32 v9, 16, v10
	v_lshlrev_b32_e32 v8, 16, v14
	v_mov_b32_e32 v12, v20
	v_mov_b32_e32 v13, v16
	v_pk_mul_f32 v[12:13], v[12:13], v[8:9]
	s_nop 0
	v_sub_f32_e32 v12, v13, v12
	v_mul_f32_e32 v27, 0x3e000000, v12
	v_mov_b32_e32 v12, v16
	v_mov_b32_e32 v13, v20
	v_pk_mul_f32 v[8:9], v[12:13], v[8:9]
	v_mov_b32_e32 v16, v21
	v_add_f32_e32 v8, v8, v9
	v_mul_f32_e32 v28, 0x3e000000, v8
	v_and_b32_e32 v9, 0xffff0000, v10
	v_and_b32_e32 v8, 0xffff0000, v14
	v_mov_b32_e32 v20, v17
	v_pk_mul_f32 v[12:13], v[16:17], v[8:9]
	v_pk_mul_f32 v[8:9], v[20:21], v[8:9]
	v_sub_f32_e32 v10, v13, v12
	v_add_f32_e32 v8, v8, v9
	v_mul_f32_e32 v16, 0x3e000000, v8
	v_lshlrev_b32_e32 v9, 16, v11
	v_lshlrev_b32_e32 v8, 16, v15
	v_mov_b32_e32 v12, v22
	v_mov_b32_e32 v13, v18
	v_pk_mul_f32 v[12:13], v[12:13], v[8:9]
	v_mul_f32_e32 v14, 0x3e000000, v10
	v_sub_f32_e32 v10, v13, v12
	v_mov_b32_e32 v12, v18
	v_mov_b32_e32 v13, v22
	v_pk_mul_f32 v[8:9], v[12:13], v[8:9]
	v_mov_b32_e32 v18, v23
	v_add_f32_e32 v8, v8, v9
	v_mul_f32_e32 v20, 0x3e000000, v8
	v_and_b32_e32 v9, 0xffff0000, v11
	v_and_b32_e32 v8, 0xffff0000, v15
	v_mul_f32_e32 v17, 0x3e000000, v10
	v_pk_mul_f32 v[10:11], v[18:19], v[8:9]
	v_mov_b32_e32 v22, v19
	v_sub_f32_e32 v10, v11, v10
	v_mul_f32_e32 v11, 0x3e000000, v10
	v_cvt_pk_bf16_f32 v10, v27, v14
	v_cvt_pk_bf16_f32 v14, v28, v16
	v_or_b32_e32 v16, s22, v70
	v_pk_mul_f32 v[8:9], v[22:23], v[8:9]
	v_cvt_pk_bf16_f32 v11, v17, v11
	v_cvt_pk_bf16_f32 v13, v24, v26
	v_mad_u64_u32 v[16:17], s[26:27], v16, s5, v[44:45]
	v_or_b32_e32 v24, s15, v70
	v_add_f32_e32 v8, v8, v9
	v_cvt_pk_bf16_f32 v9, v35, v25
	v_mad_i32_i24 v17, s21, v207, v17
	v_ashrrev_i32_e32 v25, 31, v24
	v_mul_f32_e32 v15, 0x3e000000, v8
	v_lshl_add_u64 v[16:17], v[16:17], 0, s[36:37]
	v_lshlrev_b64 v[24:25], 7, v[24:25]
	v_cvt_pk_bf16_f32 v8, v40, v36
	v_cvt_pk_bf16_f32 v12, v41, v34
	v_cvt_pk_bf16_f32 v15, v20, v15
	v_lshl_add_u64 v[20:21], v[16:17], 0, v[86:87]
	v_lshl_add_u64 v[28:29], v[64:65], 0, v[24:25]
	v_lshl_add_u64 v[40:41], v[66:67], 0, v[24:25]
	s_waitcnt vmcnt(6)
; __device__ __forceinline__ unsigned pk2(float lo, float hi) { unsigned r; asm("v_cvt_pk_bf16_f32 %0, %1, %2" : "=v"(r) : "v"(lo), "v"(hi)); return r; }
; __device__ __forceinline__ float bflo(unsigned u) { return __uint_as_float(u << 16); }
; __device__ __forceinline__ float bfhi(unsigned u) { return __uint_as_float(u & 0xffff0000u); }
; __device__ __forceinline__ void rot8(u32x4 x1, u32x4 x2, const float* cs, const float* sn, float sc, u32x4& o1, u32x4& o2) {
;     const f32x4 c0 = *(const f32x4*)cs, c1 = *(const f32x4*)(cs + 4), s0 = *(const f32x4*)sn, s1 = *(const f32x4*)(sn + 4);
;     float a[8], b[8], c[8], s[8];
;     a[0] = bflo(x1.x); a[1] = bfhi(x1.x); a[2] = bflo(x1.y); a[3] = bfhi(x1.y); a[4] = bflo(x1.z); a[5] = bfhi(x1.z); a[6] = bflo(x1.w); a[7] = bfhi(x1.w);
;     b[0] = bflo(x2.x); b[1] = bfhi(x2.x); b[2] = bflo(x2.y); b[3] = bfhi(x2.y); b[4] = bflo(x2.z); b[5] = bfhi(x2.z); b[6] = bflo(x2.w); b[7] = bfhi(x2.w);
; #pragma unroll
;     for (int i = 0; i < 4; ++i) { c[i] = c0[i]; c[4 + i] = c1[i]; s[i] = s0[i]; s[4 + i] = s1[i]; }
;     float p[8], q[8];
; #pragma unroll
;     for (int i = 0; i < 8; ++i) { p[i] = (a[i] * c[i] - b[i] * s[i]) * sc; q[i] = (a[i] * s[i] + b[i] * c[i]) * sc; }
;     o1.x = pk2(p[0], p[1]); o1.y = pk2(p[2], p[3]); o1.z = pk2(p[4], p[5]); o1.w = pk2(p[6], p[7]);
;     o2.x = pk2(q[0], q[1]); o2.y = pk2(q[2], q[3]); o2.z = pk2(q[4], q[5]); o2.w = pk2(q[6], q[7]);
; }
; __device__ __forceinline__ void retout_item(const bf16_t* hbuf, const float* rot, const float* kvbuf, const float* normg, bf16_t* mixed, LAS bf16_t* vT, int item, int lane) {
;     ...
;     for (int mt = 0; mt < 4; ++mt) { const int row = 16 * mt + r; const bf16_t* kp = hbuf + (t0 + row) * INWP + C_RK + h * 64 + 8 * q; const int pos = n * 64 + row; u32x4 o1, o2;
;         rot8(*(const u32x4*)kp, *(const u32x4*)(kp + 32), cs + (size_t)pos * 32 + 8 * q, sn + (size_t)pos * 32 + 8 * q, 0.125f, o1, o2); kf[mt][0] = as_bf16x8(o1); kf[mt][1] = as_bf16x8(o2); }
	v_mov_b64_e32 v[16:17], v[196:197]
	v_mov_b64_e32 v[18:19], v[198:199]
	v_mov_b64_e32 v[20:21], v[200:201]
	v_mov_b64_e32 v[22:23], v[202:203]
	v_mov_b64_e32 v[24:25], v[212:213]
	v_mov_b64_e32 v[26:27], v[214:215]
	v_mov_b64_e32 v[34:35], v[216:217]
	v_mov_b64_e32 v[36:37], v[218:219]
	v_mov_b64_e32 v[28:29], v[220:221]
	v_mov_b64_e32 v[30:31], v[222:223]
	v_mov_b64_e32 v[40:41], v[224:225]
	v_mov_b64_e32 v[42:43], v[226:227]
	v_lshlrev_b32_e32 v47, 16, v16
	v_lshlrev_b32_e32 v46, 16, v20
	v_mov_b32_e32 v48, v40
	v_mov_b32_e32 v49, v34
	v_pk_mul_f32 v[48:49], v[48:49], v[46:47]
	s_nop 0
	v_sub_f32_e32 v48, v49, v48
	v_mul_f32_e32 v50, 0x3e000000, v48
	v_mov_b32_e32 v48, v34
	v_mov_b32_e32 v49, v40
	v_pk_mul_f32 v[46:47], v[48:49], v[46:47]
	v_mov_b32_e32 v40, v35
	v_add_f32_e32 v34, v46, v47
	v_mul_f32_e32 v51, 0x3e000000, v34
	v_and_b32_e32 v47, 0xffff0000, v16
	v_and_b32_e32 v46, 0xffff0000, v20
	v_mov_b32_e32 v34, v41
	v_pk_mul_f32 v[48:49], v[34:35], v[46:47]
	v_pk_mul_f32 v[34:35], v[40:41], v[46:47]
	v_sub_f32_e32 v16, v49, v48
	v_mul_f32_e32 v48, 0x3e000000, v16
	v_add_f32_e32 v16, v34, v35
	v_lshlrev_b32_e32 v35, 16, v17
	v_lshlrev_b32_e32 v34, 16, v21
	v_mov_b32_e32 v40, v42
	v_mov_b32_e32 v41, v36
	v_pk_mul_f32 v[40:41], v[40:41], v[34:35]
	v_mul_f32_e32 v46, 0x3e000000, v16
	v_sub_f32_e32 v16, v41, v40
	v_mov_b32_e32 v40, v36
	v_mov_b32_e32 v41, v42
	v_pk_mul_f32 v[34:35], v[40:41], v[34:35]
	v_mul_f32_e32 v47, 0x3e000000, v16
	v_add_f32_e32 v16, v34, v35
	v_mul_f32_e32 v34, 0x3e000000, v16
	v_and_b32_e32 v17, 0xffff0000, v17
	v_and_b32_e32 v16, 0xffff0000, v21
	v_mov_b32_e32 v36, v43
	v_mov_b32_e32 v42, v37
	v_pk_mul_f32 v[20:21], v[36:37], v[16:17]
	v_pk_mul_f32 v[16:17], v[42:43], v[16:17]
	v_sub_f32_e32 v20, v21, v20
	v_add_f32_e32 v16, v16, v17
	v_mul_f32_e32 v35, 0x3e000000, v20
	v_mul_f32_e32 v36, 0x3e000000, v16
	v_lshlrev_b32_e32 v17, 16, v18
	v_lshlrev_b32_e32 v16, 16, v22
	v_mov_b32_e32 v20, v28
	v_mov_b32_e32 v21, v24
	v_pk_mul_f32 v[20:21], v[20:21], v[16:17]
	s_nop 0
	v_sub_f32_e32 v20, v21, v20
	v_mul_f32_e32 v37, 0x3e000000, v20
	v_mov_b32_e32 v20, v24
	v_mov_b32_e32 v21, v28
	v_pk_mul_f32 v[16:17], v[20:21], v[16:17]
	v_mov_b32_e32 v24, v29
	v_add_f32_e32 v16, v16, v17
	v_mul_f32_e32 v40, 0x3e000000, v16
	v_and_b32_e32 v17, 0xffff0000, v18
	v_and_b32_e32 v16, 0xffff0000, v22
	v_mov_b32_e32 v28, v25
	v_pk_mul_f32 v[20:21], v[24:25], v[16:17]
	v_pk_mul_f32 v[16:17], v[28:29], v[16:17]
	v_sub_f32_e32 v18, v21, v20
	v_add_f32_e32 v16, v16, v17
	v_mul_f32_e32 v24, 0x3e000000, v16
	v_lshlrev_b32_e32 v17, 16, v19
	v_lshlrev_b32_e32 v16, 16, v23
	v_mov_b32_e32 v20, v30
	v_mov_b32_e32 v21, v26
	v_pk_mul_f32 v[20:21], v[20:21], v[16:17]
	v_mul_f32_e32 v22, 0x3e000000, v18
	v_sub_f32_e32 v18, v21, v20
	v_mov_b32_e32 v20, v26
	v_mov_b32_e32 v21, v30
	v_pk_mul_f32 v[16:17], v[20:21], v[16:17]
	v_mov_b32_e32 v26, v31
	v_add_f32_e32 v16, v16, v17
	v_mul_f32_e32 v28, 0x3e000000, v16
	v_and_b32_e32 v17, 0xffff0000, v19
	v_and_b32_e32 v16, 0xffff0000, v23
	v_mul_f32_e32 v25, 0x3e000000, v18
	v_pk_mul_f32 v[18:19], v[26:27], v[16:17]
	v_mov_b32_e32 v30, v27
	v_sub_f32_e32 v18, v19, v18
	v_mul_f32_e32 v19, 0x3e000000, v18
	v_cvt_pk_bf16_f32 v18, v37, v22
	v_cvt_pk_bf16_f32 v22, v40, v24
	v_or_b32_e32 v24, s22, v72
	v_pk_mul_f32 v[16:17], v[30:31], v[16:17]
	v_cvt_pk_bf16_f32 v19, v25, v19
	v_cvt_pk_bf16_f32 v21, v34, v36
	v_mad_u64_u32 v[24:25], s[22:23], v24, s5, v[44:45]
	v_or_b32_e32 v34, s15, v72
	v_add_f32_e32 v16, v16, v17
	v_cvt_pk_bf16_f32 v17, v47, v35
	v_mad_i32_i24 v25, s21, v207, v25
	v_ashrrev_i32_e32 v35, 31, v34
	v_mul_f32_e32 v23, 0x3e000000, v16
	v_lshl_add_u64 v[24:25], v[24:25], 0, s[36:37]
	v_lshlrev_b64 v[34:35], 7, v[34:35]
	v_cvt_pk_bf16_f32 v16, v50, v48
	v_cvt_pk_bf16_f32 v23, v28, v23
	v_lshl_add_u64 v[28:29], v[24:25], 0, v[86:87]
	v_lshl_add_u64 v[40:41], v[64:65], 0, v[34:35]
	v_lshl_add_u64 v[48:49], v[66:67], 0, v[34:35]
	v_cvt_pk_bf16_f32 v20, v51, v46
	s_waitcnt vmcnt(0)
; #define LAS __attribute__((address_space(3)))
; __device__ __forceinline__ unsigned pk2(float lo, float hi) { unsigned r; asm("v_cvt_pk_bf16_f32 %0, %1, %2" : "=v"(r) : "v"(lo), "v"(hi)); return r; }
; __device__ __forceinline__ void lds_fence() { asm volatile("s_waitcnt lgkmcnt(0)" ::: "memory"); }
; __device__ __forceinline__ void retout_item(const bf16_t* hbuf, const float* rot, const float* kvbuf, const float* normg, bf16_t* mixed, LAS bf16_t* vT, int item, int lane) {
;     ...
;     for (int mt = 0; mt < 4; ++mt) { const int row = 16 * mt + r; const bf16_t* kp = hbuf + (t0 + row) * INWP + C_RK + h * 64 + 8 * q; const int pos = n * 64 + row; u32x4 o1, o2;
;         rot8(*(const u32x4*)kp, *(const u32x4*)(kp + 32), cs + (size_t)pos * 32 + 8 * q, sn + (size_t)pos * 32 + 8 * q, 0.125f, o1, o2); kf[mt][0] = as_bf16x8(o1); kf[mt][1] = as_bf16x8(o2); }
;     const float* Rp = kvbuf + (size_t)item * 4096;
; #pragma unroll
;     for (int et = 0; et < 4; ++et)
; #pragma unroll
;         for (int ks = 0; ks < 2; ++ks) { const float* p = Rp + (16 * et + r) * 64 + 32 * ks + 8 * q; const f32x4 a = *(const f32x4*)p, c = *(const f32x4*)(p + 4);
;             *(LAS u32x4*)(RT + (16 * et + r) * TLD + 32 * ks + 8 * q) = (u32x4){pk2(a[0], a[1]), pk2(a[2], a[3]), pk2(c[0], c[1]), pk2(c[2], c[3])}; }
;     lds_fence();
	v_mov_b64_e32 v[24:25], v[172:173]
	v_mov_b64_e32 v[26:27], v[174:175]
	v_mov_b64_e32 v[28:29], v[176:177]
	v_mov_b64_e32 v[30:31], v[178:179]
	v_mov_b64_e32 v[34:35], v[180:181]
	v_mov_b64_e32 v[36:37], v[182:183]
	v_mov_b64_e32 v[44:45], v[184:185]
	v_mov_b64_e32 v[46:47], v[186:187]
	v_mov_b64_e32 v[40:41], v[188:189]
	v_mov_b64_e32 v[42:43], v[190:191]
	v_mov_b64_e32 v[48:49], v[192:193]
	v_mov_b64_e32 v[50:51], v[194:195]
	s_lshl_b64 s[22:23], s[0:1], 14
	v_lshlrev_b32_e32 v55, 16, v24
	v_lshlrev_b32_e32 v54, 16, v28
	v_mov_b32_e32 v56, v48
	v_mov_b32_e32 v57, v44
	v_pk_mul_f32 v[56:57], v[56:57], v[54:55]
	s_nop 0
	v_sub_f32_e32 v56, v57, v56
	v_mul_f32_e32 v58, 0x3e000000, v56
	v_mov_b32_e32 v56, v44
	v_mov_b32_e32 v57, v48
	v_pk_mul_f32 v[54:55], v[56:57], v[54:55]
	v_mov_b32_e32 v48, v45
	v_add_f32_e32 v44, v54, v55
	v_mul_f32_e32 v59, 0x3e000000, v44
	v_and_b32_e32 v55, 0xffff0000, v24
	v_and_b32_e32 v54, 0xffff0000, v28
	v_mov_b32_e32 v44, v49
	v_pk_mul_f32 v[56:57], v[44:45], v[54:55]
	v_pk_mul_f32 v[44:45], v[48:49], v[54:55]
	v_sub_f32_e32 v24, v57, v56
	v_mul_f32_e32 v56, 0x3e000000, v24
	v_add_f32_e32 v24, v44, v45
	v_lshlrev_b32_e32 v45, 16, v25
	v_lshlrev_b32_e32 v44, 16, v29
	v_mov_b32_e32 v48, v50
	v_mov_b32_e32 v49, v46
	v_pk_mul_f32 v[48:49], v[48:49], v[44:45]
	v_mul_f32_e32 v54, 0x3e000000, v24
	v_sub_f32_e32 v24, v49, v48
	v_mov_b32_e32 v48, v46
	v_mov_b32_e32 v49, v50
	v_pk_mul_f32 v[44:45], v[48:49], v[44:45]
	v_mul_f32_e32 v55, 0x3e000000, v24
	v_add_f32_e32 v24, v44, v45
	v_mul_f32_e32 v44, 0x3e000000, v24
	v_and_b32_e32 v25, 0xffff0000, v25
	v_and_b32_e32 v24, 0xffff0000, v29
	v_mov_b32_e32 v46, v51
	v_mov_b32_e32 v50, v47
	v_pk_mul_f32 v[28:29], v[46:47], v[24:25]
	v_pk_mul_f32 v[24:25], v[50:51], v[24:25]
	v_sub_f32_e32 v28, v29, v28
	v_add_f32_e32 v24, v24, v25
	v_mul_f32_e32 v45, 0x3e000000, v28
	v_mul_f32_e32 v46, 0x3e000000, v24
	v_lshlrev_b32_e32 v25, 16, v26
	v_lshlrev_b32_e32 v24, 16, v30
	v_mov_b32_e32 v28, v40
	v_mov_b32_e32 v29, v34
	v_pk_mul_f32 v[28:29], v[28:29], v[24:25]
	s_nop 0
	v_sub_f32_e32 v28, v29, v28
	v_mul_f32_e32 v47, 0x3e000000, v28
	v_mov_b32_e32 v28, v34
	v_mov_b32_e32 v29, v40
	v_pk_mul_f32 v[24:25], v[28:29], v[24:25]
	v_mov_b32_e32 v34, v41
	v_add_f32_e32 v24, v24, v25
	v_mul_f32_e32 v48, 0x3e000000, v24
	v_and_b32_e32 v25, 0xffff0000, v26
	v_and_b32_e32 v24, 0xffff0000, v30
	v_mov_b32_e32 v40, v35
	v_pk_mul_f32 v[28:29], v[34:35], v[24:25]
	v_pk_mul_f32 v[24:25], v[40:41], v[24:25]
	v_sub_f32_e32 v26, v29, v28
	v_add_f32_e32 v24, v24, v25
	v_mul_f32_e32 v34, 0x3e000000, v24
	v_lshlrev_b32_e32 v25, 16, v27
	v_lshlrev_b32_e32 v24, 16, v31
	v_mov_b32_e32 v28, v42
	v_mov_b32_e32 v29, v36
	v_pk_mul_f32 v[28:29], v[28:29], v[24:25]
	v_mul_f32_e32 v30, 0x3e000000, v26
	v_sub_f32_e32 v26, v29, v28
	v_mov_b32_e32 v28, v36
	v_mov_b32_e32 v29, v42
	v_pk_mul_f32 v[24:25], v[28:29], v[24:25]
	v_mov_b32_e32 v36, v43
	v_add_f32_e32 v24, v24, v25
	v_mul_f32_e32 v40, 0x3e000000, v24
	v_and_b32_e32 v25, 0xffff0000, v27
	v_and_b32_e32 v24, 0xffff0000, v31
	v_mul_f32_e32 v35, 0x3e000000, v26
	v_pk_mul_f32 v[26:27], v[36:37], v[24:25]
	v_mov_b32_e32 v42, v37
	v_sub_f32_e32 v26, v27, v26
	v_mul_f32_e32 v27, 0x3e000000, v26
	v_pk_mul_f32 v[24:25], v[42:43], v[24:25]
	v_cvt_pk_bf16_f32 v26, v47, v30
	v_cvt_pk_bf16_f32 v27, v35, v27
	v_cvt_pk_bf16_f32 v30, v48, v34
	v_lshl_add_u64 v[34:35], v[74:75], 0, s[22:23]
	v_add_f32_e32 v24, v24, v25
	v_mul_f32_e32 v31, 0x3e000000, v24
	v_cvt_pk_bf16_f32 v25, v55, v45
	v_cvt_pk_bf16_f32 v29, v44, v46
	v_cvt_pk_bf16_f32 v31, v40, v31
	v_lshl_add_u64 v[144:145], v[34:35], 0, v[88:89]
	v_lshl_add_u64 v[146:147], v[34:35], 0, v[90:91]
	v_lshl_add_u64 v[148:149], v[34:35], 0, v[92:93]
	v_lshl_add_u64 v[150:151], v[34:35], 0, v[94:95]
	global_load_dwordx4 v[172:175], v[144:145], off
	global_load_dwordx4 v[176:179], v[144:145], off offset:16
	global_load_dwordx4 v[180:183], v[144:145], off offset:128
	global_load_dwordx4 v[184:187], v[144:145], off offset:144
	global_load_dwordx4 v[188:191], v[146:147], off
	global_load_dwordx4 v[192:195], v[146:147], off offset:16
	global_load_dwordx4 v[196:199], v[146:147], off offset:128
	global_load_dwordx4 v[200:203], v[146:147], off offset:144
	global_load_dwordx4 v[212:215], v[148:149], off
	global_load_dwordx4 v[216:219], v[148:149], off offset:16
	global_load_dwordx4 v[220:223], v[148:149], off offset:128
	global_load_dwordx4 v[224:227], v[148:149], off offset:144
	global_load_dwordx4 v[152:155], v[150:151], off
	global_load_dwordx4 v[156:159], v[150:151], off offset:16
	global_load_dwordx4 v[160:163], v[150:151], off offset:128
	global_load_dwordx4 v[232:235], v[150:151], off offset:144
	s_and_b64 s[22:23], vcc, exec
	s_cselect_b32 s1, 32, 0
	v_ldexp_f32 v34, v53, s1
	v_log_f32_e32 v34, v34
	s_waitcnt vmcnt(14)
	v_cvt_pk_bf16_f32 v172, v172, v173
	v_cvt_pk_bf16_f32 v173, v174, v175
	v_cvt_pk_bf16_f32 v174, v176, v177
	v_cvt_pk_bf16_f32 v175, v178, v179
	ds_write_b128 v63, v[172:175] offset:9216
	s_waitcnt vmcnt(12)
	v_cvt_pk_bf16_f32 v180, v180, v181
	v_cvt_pk_bf16_f32 v181, v182, v183
	v_cvt_pk_bf16_f32 v182, v184, v185
	v_cvt_pk_bf16_f32 v183, v186, v187
	ds_write_b128 v63, v[180:183] offset:9280
	s_waitcnt vmcnt(10)
	v_cvt_pk_bf16_f32 v188, v188, v189
	v_cvt_pk_bf16_f32 v189, v190, v191
	v_cvt_pk_bf16_f32 v190, v192, v193
	v_cvt_pk_bf16_f32 v191, v194, v195
	ds_write_b128 v63, v[188:191] offset:11520
	s_waitcnt vmcnt(8)
	v_cvt_pk_bf16_f32 v196, v196, v197
	v_cvt_pk_bf16_f32 v197, v198, v199
	v_cvt_pk_bf16_f32 v198, v200, v201
	v_cvt_pk_bf16_f32 v199, v202, v203
	ds_write_b128 v63, v[196:199] offset:11584
	s_waitcnt vmcnt(6)
	v_cvt_pk_bf16_f32 v212, v212, v213
	v_cvt_pk_bf16_f32 v213, v214, v215
	v_cvt_pk_bf16_f32 v214, v216, v217
	v_cvt_pk_bf16_f32 v215, v218, v219
	ds_write_b128 v63, v[212:215] offset:13824
	s_waitcnt vmcnt(4)
	v_cvt_pk_bf16_f32 v220, v220, v221
	v_cvt_pk_bf16_f32 v221, v222, v223
	v_cvt_pk_bf16_f32 v222, v224, v225
	v_cvt_pk_bf16_f32 v223, v226, v227
	ds_write_b128 v63, v[220:223] offset:13888
	s_waitcnt vmcnt(2)
	v_cvt_pk_bf16_f32 v152, v152, v153
	v_cvt_pk_bf16_f32 v153, v154, v155
	v_cvt_pk_bf16_f32 v154, v156, v157
	v_cvt_pk_bf16_f32 v155, v158, v159
	ds_write_b128 v128, v[152:155] offset:9216
	s_waitcnt vmcnt(0)
	v_cvt_pk_bf16_f32 v160, v160, v161
	v_cvt_pk_bf16_f32 v161, v162, v163
	v_cvt_pk_bf16_f32 v162, v232, v233
	v_cvt_pk_bf16_f32 v163, v234, v235
	ds_write_b128 v128, v[160:163] offset:9280
	v_cndmask_b32_e32 v35, 0, v246, vcc
	v_sub_f32_e32 v85, v34, v35
	s_waitcnt lgkmcnt(0)
	v_lshl_or_b32 v34, s0, 6, v60
	s_lshl_b32 s1, s17, 14
	v_mov_b32_e32 v53, s21
	v_subrev_u32_e32 v87, s1, v34
	v_mad_u64_u32 v[98:99], s[22:23], v52, s5, v[78:79]
	v_mad_u64_u32 v[100:101], s[22:23], v52, s5, v[80:81]
	v_lshlrev_b64 v[34:35], 11, v[52:53]
	v_mad_i32_i24 v99, s21, v207, v99
	v_mad_i32_i24 v101, s21, v207, v101
	v_lshl_add_u64 v[102:103], v[82:83], 0, v[34:35]
	v_mov_b32_e32 v91, v126
	v_cvt_pk_bf16_f32 v24, v58, v56
	v_cvt_pk_bf16_f32 v28, v59, v54
